# rwkv2 role-2 pulls the rows of chunk pc+3 (instead of pc+4)
# baseline (speedup 1.0000x reference)
; __device__ unsigned long long rwkv2_phase(const Params& p, unsigned char* smem) {
;     ...
;             for (int pc = 0; pc <= NCH + 1; ++pc) {
;                 const int cs = pc - 2; const bool act = (cs >= 0 && cs < NCH); const bool doY = act && ((cs & 1) == ws);
;                 int ln_ = lane; asm volatile("" : "+v"(ln_)); const int lane = ln_, l15 = ln_ & 15, lq = ln_ >> 4; (void)lane;
.LBB0_922:
	s_waitcnt lgkmcnt(0)
	s_barrier
	s_add_i32 s40, s30, 3
	s_cmpk_gt_u32 s40, 0xff
	s_cbranch_scc1 RWPULL_skip
	v_readlane_b32 s38, v251, 36
	v_readlane_b32 s39, v251, 37
	s_lshl_b32 s41, s40, 17
	s_mul_i32 s42, s40, 0x3000
	v_add_u32_e32 v235, s41, v244
	v_add_u32_e32 v236, s41, v245
	v_add_u32_e32 v237, s41, v246
	v_add_u32_e32 v238, s41, v247
	v_add_u32_e32 v239, s42, v248
	global_load_dwordx4 v[240:243], v235, s[38:39]
	global_load_dwordx4 v[240:243], v236, s[38:39]
	global_load_dwordx4 v[240:243], v237, s[38:39]
	global_load_dwordx4 v[240:243], v238, s[38:39]
	global_load_dwordx4 v[240:243], v239, s[38:39]
	global_load_dwordx4 v[240:243], v239, s[38:39] offset:1024
	global_load_dwordx4 v[240:243], v239, s[38:39] offset:2048
	global_load_dwordx4 v[240:243], v239, s[38:39] offset:3072
	v_add_u32_e32 v239, 0x1000, v239
	global_load_dwordx4 v[240:243], v239, s[38:39]
	global_load_dwordx4 v[240:243], v239, s[38:39] offset:1024
